# weight copies of layers 1-3 moved from prologue into in-proj tail rounds (idle CUs)
# speedup vs baseline: 1.0501x; 1.0015x over previous
.LBB0_1209:
	v_readlane_b32 s72, v254, 63
	v_readlane_b32 s56, v255, 19
	v_readlane_b32 s73, v255, 0
	v_readlane_b32 s74, v255, 1
	v_readlane_b32 s75, v255, 2
	v_readlane_b32 s76, v255, 3
	v_readlane_b32 s77, v255, 4
	v_readlane_b32 s78, v255, 5
	v_readlane_b32 s79, v255, 6
	v_readlane_b32 s80, v255, 7
	v_readlane_b32 s81, v255, 8
	v_readlane_b32 s82, v255, 9
	v_readlane_b32 s83, v255, 10
	v_readlane_b32 s84, v255, 11
	v_readlane_b32 s85, v255, 12
	v_readlane_b32 s86, v255, 13
	v_readlane_b32 s87, v255, 14
	v_readlane_b32 s57, v255, 20
	s_movk_i32 s60, 0x1000
	v_readlane_b32 s61, v255, 23
	s_cmp_eq_u32 s61, 2
	s_cbranch_scc1 .Lwc_l0
	s_cmp_eq_u32 s61, 8
	s_cbranch_scc1 .Lwc_l1
	s_cmp_eq_u32 s61, 14
	s_cbranch_scc1 .Lwc_l2
	s_branch .LBB0_1350
.Lwc_l0:
	s_movk_i32 s101, 0x1420
	s_movk_i32 s100, 0x2c3f
	s_branch .Lwc_go
.Lwc_l1:
	s_movk_i32 s101, 0x2a40
	s_movk_i32 s100, 0x425f
	s_branch .Lwc_go
.Lwc_l2:
	s_movk_i32 s101, 0x4060
	s_movk_i32 s100, 0x587f
.Lwc_go:
	v_readlane_b32 s6, v254, 31
	s_nop 0
	s_cmpk_lt_u32 s6, 0x200
	s_cbranch_scc1 .LBB0_1350
	s_movk_i32 s16, 0xc0
	v_readfirstlane_b32 s17, v186
	v_and_b32_e32 v40, 31, v186
	s_branch .Lwc_entry
.LBB0_1210:
	s_movk_i32 s100, 0x161f
	s_mov_b32 s101, 0
	s_movk_i32 s0, 0x2400
	v_readfirstlane_b32 s17, v186
	s_mov_b32 s16, s3
	v_cmp_gt_i32_e32 vcc, s0, v186
	s_and_saveexec_b64 s[6:7], vcc
	s_cbranch_execz .LBB0_1222
	v_max_i32_e32 v0, 0x2200, v186
	v_sub_u32_e32 v0, v0, v186
	s_waitcnt lgkmcnt(0)
	v_add_u32_e32 v1, 0x1ff, v0
	s_movk_i32 s0, 0x1ff
	v_cmp_lt_u32_e32 vcc, s0, v1
	s_mov_b64 s[0:1], -1
	v_mov_b32_e32 v0, v186
	s_and_saveexec_b64 s[8:9], vcc
	s_cbranch_execz .LBB0_1219
	v_lshrrev_b32_e32 v2, 9, v1
	v_add_u32_e32 v187, 0x200, v186
	v_add_u32_e32 v3, -1, v2
	v_cmp_lt_u32_e32 vcc, 1, v3
	v_mov_b32_e32 v4, 0
	v_mov_b64_e32 v[0:1], v[186:187]
	s_and_saveexec_b64 s[10:11], vcc
	s_cbranch_execz .LBB0_1216
	v_lshrrev_b32_e32 v0, 1, v3
	v_add_u32_e32 v0, 1, v0
	v_readlane_b32 s40, v252, 21
	v_and_b32_e32 v4, -2, v0
	v_lshl_add_u32 v5, v186, 2, 0
	s_mov_b32 s14, 0
	s_mov_b64 s[12:13], 0
	v_mov_b64_e32 v[0:1], v[186:187]
	v_readlane_b32 s42, v252, 23
	v_readlane_b32 s43, v252, 24
	v_readlane_b32 s46, v252, 27
	v_readlane_b32 s47, v252, 28
	s_movk_i32 s15, 0x2000
	s_mov_b32 s20, 0xbfb8aa3b
	s_mov_b32 s21, 0x42ce8ed0
	s_mov_b32 s24, 0xc2b17218
	v_readlane_b32 s41, v252, 22
	v_readlane_b32 s44, v252, 25
	v_readlane_b32 s45, v252, 26
	v_readlane_b32 s48, v252, 29
	v_readlane_b32 s49, v252, 30
	v_readlane_b32 s50, v252, 31
	v_readlane_b32 s51, v252, 32
	v_readlane_b32 s52, v252, 33
	v_readlane_b32 s53, v252, 34
	v_readlane_b32 s54, v252, 35
	v_readlane_b32 s55, v252, 36

.Lwc_entry:
	s_ashr_i32 s0, s17, 6
	v_readlane_b32 s6, v254, 31
	s_add_i32 s12, s0, s6
	s_add_i32 s12, s12, s101
	s_cmp_gt_i32 s12, s100
	v_readlane_b32 s7, v254, 32
	s_cbranch_scc1 .LBB0_1350
	v_lshlrev_b32_e32 v1, 3, v186
	s_lshl_b32 s0, s0, 14
	v_bfe_u32 v0, v186, 5, 1
	v_bfe_u32 v41, v186, 3, 3
	v_and_b32_e32 v2, 56, v1
	s_add_i32 s1, s0, 0
	v_mul_u32_u24_e32 v1, 0x84, v2
	v_lshlrev_b32_e32 v3, 2, v41
	v_mul_u32_u24_e32 v84, 0x84, v0
	v_lshlrev_b32_e32 v36, 2, v40
	v_add3_u32 v80, s1, v1, v3
	v_or_b32_e32 v1, 2, v0
	v_or_b32_e32 v3, 6, v0
	v_or_b32_e32 v4, 4, v0
	v_or_b32_e32 v5, 10, v0
	v_or_b32_e32 v6, 8, v0
	v_or_b32_e32 v7, 14, v0
	v_or_b32_e32 v8, 12, v0
	v_or_b32_e32 v9, 18, v0
	v_or_b32_e32 v10, 16, v0
	v_or_b32_e32 v11, 22, v0
	v_or_b32_e32 v12, 20, v0
	v_or_b32_e32 v13, 26, v0
	v_or_b32_e32 v14, 24, v0
	v_or_b32_e32 v15, 30, v0
	v_or_b32_e32 v16, 28, v0
	v_or_b32_e32 v17, 34, v0
	v_or_b32_e32 v18, 32, v0
	v_or_b32_e32 v19, 38, v0
	v_or_b32_e32 v20, 36, v0
	v_or_b32_e32 v21, 42, v0
	v_or_b32_e32 v22, 40, v0
	v_or_b32_e32 v23, 46, v0
	v_or_b32_e32 v24, 44, v0
	v_or_b32_e32 v25, 50, v0
	v_or_b32_e32 v26, 48, v0
	v_or_b32_e32 v27, 54, v0
	v_or_b32_e32 v28, 52, v0
	v_or_b32_e32 v29, 58, v0
	v_or_b32_e32 v30, 56, v0
	v_or_b32_e32 v31, 62, v0
	v_or_b32_e32 v32, 60, v0
	v_or_b32_e32 v34, s0, v84
	v_mov_b32_e32 v37, v99
	v_lshlrev_b32_e32 v38, 2, v0
	v_mov_b32_e32 v39, v99
	s_lshl_b32 s13, s16, 3
	v_add_u32_e32 v33, s1, v36
	v_or_b32_e32 v81, 8, v41
	v_or_b32_e32 v82, 16, v41
	v_or_b32_e32 v83, 24, v41
	v_mul_u32_u24_e32 v85, 0x84, v1
	v_mul_u32_u24_e32 v86, 0x84, v4
	v_mul_u32_u24_e32 v87, 0x84, v3
	v_mul_u32_u24_e32 v88, 0x84, v6
	v_mul_u32_u24_e32 v89, 0x84, v5
	v_mul_u32_u24_e32 v90, 0x84, v8
	v_mul_u32_u24_e32 v91, 0x84, v7
	v_mul_u32_u24_e32 v92, 0x84, v10
	v_mul_u32_u24_e32 v93, 0x84, v9
	v_mul_u32_u24_e32 v94, 0x84, v12
	v_mul_u32_u24_e32 v95, 0x84, v11
	v_mul_u32_u24_e32 v96, 0x84, v14
	v_mul_u32_u24_e32 v97, 0x84, v13
	v_mul_u32_u24_e32 v100, 0x84, v16
	v_mul_u32_u24_e32 v101, 0x84, v15
	v_mul_u32_u24_e32 v102, 0x84, v18
	v_mul_u32_u24_e32 v103, 0x84, v17
	v_mul_u32_u24_e32 v104, 0x84, v20
	v_mul_u32_u24_e32 v105, 0x84, v19
	v_mul_u32_u24_e32 v106, 0x84, v22
	v_mul_u32_u24_e32 v107, 0x84, v21
	v_mul_u32_u24_e32 v108, 0x84, v24
	v_mul_u32_u24_e32 v109, 0x84, v23
	v_mul_u32_u24_e32 v110, 0x84, v26
	v_mul_u32_u24_e32 v111, 0x84, v25
	v_mul_u32_u24_e32 v112, 0x84, v28
	v_mul_u32_u24_e32 v113, 0x84, v27
	v_mul_u32_u24_e32 v114, 0x84, v30
	v_mul_u32_u24_e32 v115, 0x84, v29
	v_mul_u32_u24_e32 v116, 0x84, v32
	v_mul_u32_u24_e32 v117, 0x84, v31
	v_add3_u32 v118, v34, v36, 0
	v_lshl_add_u64 v[34:35], s[84:85], 0, v[36:37]
	v_lshl_add_u64 v[36:37], s[80:81], 0, v[36:37]
	v_lshl_add_u64 v[38:39], s[78:79], 0, v[38:39]
	s_branch .LBB0_1262
.LBB0_1261:
	s_add_i32 s12, s12, s13
	s_cmp_gt_i32 s12, s100
	s_cbranch_scc1 .LBB0_1350

	.amdhsa_kernel _Z6mk_fwd4Args
		.amdhsa_group_segment_fixed_size 0
		.amdhsa_private_segment_fixed_size 0
		.amdhsa_kernarg_size 432
		.amdhsa_user_sgpr_count 2
		.amdhsa_user_sgpr_dispatch_ptr 0
		.amdhsa_user_sgpr_queue_ptr 0
		.amdhsa_user_sgpr_kernarg_segment_ptr 1
		.amdhsa_user_sgpr_dispatch_id 0
		.amdhsa_user_sgpr_kernarg_preload_length 0
		.amdhsa_user_sgpr_kernarg_preload_offset 0
		.amdhsa_user_sgpr_private_segment_size 0
		.amdhsa_uses_dynamic_stack 0
		.amdhsa_enable_private_segment 0
		.amdhsa_system_sgpr_workgroup_id_x 1
		.amdhsa_system_sgpr_workgroup_id_y 0
		.amdhsa_system_sgpr_workgroup_id_z 0
		.amdhsa_system_sgpr_workgroup_info 0
		.amdhsa_system_vgpr_workitem_id 2
		.amdhsa_next_free_vgpr 256
		.amdhsa_next_free_sgpr 102
		.amdhsa_accum_offset 256
		.amdhsa_reserve_vcc 1
		.amdhsa_float_round_mode_32 0
		.amdhsa_float_round_mode_16_64 0
		.amdhsa_float_denorm_mode_32 3
		.amdhsa_float_denorm_mode_16_64 3
		.amdhsa_dx10_clamp 1
		.amdhsa_ieee_mode 1
		.amdhsa_fp16_overflow 0
		.amdhsa_tg_split 0
		.amdhsa_exception_fp_ieee_invalid_op 0
		.amdhsa_exception_fp_denorm_src 0
		.amdhsa_exception_fp_ieee_div_zero 0
		.amdhsa_exception_fp_ieee_overflow 0
		.amdhsa_exception_fp_ieee_underflow 0
		.amdhsa_exception_fp_ieee_inexact 0
		.amdhsa_exception_int_div_zero 0
	.end_amdhsa_kernel

amdhsa.kernels:
  - .agpr_count:     0
    .args:
      - .offset:         0
        .size:           176
        .value_kind:     by_value
      - .offset:         176
        .size:           4
        .value_kind:     hidden_block_count_x
      - .offset:         180
        .size:           4
        .value_kind:     hidden_block_count_y
      - .offset:         184
        .size:           4
        .value_kind:     hidden_block_count_z
      - .offset:         188
        .size:           2
        .value_kind:     hidden_group_size_x
      - .offset:         190
        .size:           2
        .value_kind:     hidden_group_size_y
      - .offset:         192
        .size:           2
        .value_kind:     hidden_group_size_z
      - .offset:         194
        .size:           2
        .value_kind:     hidden_remainder_x
      - .offset:         196
        .size:           2
        .value_kind:     hidden_remainder_y
      - .offset:         198
        .size:           2
        .value_kind:     hidden_remainder_z
      - .offset:         216
        .size:           8
        .value_kind:     hidden_global_offset_x
      - .offset:         224
        .size:           8
        .value_kind:     hidden_global_offset_y
      - .offset:         232
        .size:           8
        .value_kind:     hidden_global_offset_z
      - .offset:         240
        .size:           2
        .value_kind:     hidden_grid_dims
      - .offset:         264
        .size:           8
        .value_kind:     hidden_multigrid_sync_arg
      - .offset:         296
        .size:           4
        .value_kind:     hidden_dynamic_lds_size
    .group_segment_fixed_size: 0
    .kernarg_segment_align: 8
    .kernarg_segment_size: 432
    .language:       OpenCL C
    .language_version:
      - 2
      - 0
    .max_flat_workgroup_size: 512
    .name:           _Z6mk_fwd4Args
    .private_segment_fixed_size: 0
    .sgpr_count:     108
    .sgpr_spill_count: 387
    .symbol:         _Z6mk_fwd4Args.kd
    .uniform_work_group_size: 1
    .uses_dynamic_stack: false
    .vgpr_count:     256
    .vgpr_spill_count: 0
    .wavefront_size: 64
